# P6 gdn_local: Q-fragment loads of both QK^T blocks issued together (8 in flight) instead of one-at-a-time behind vmcnt(0)
# speedup vs baseline: 1.0017x; 1.0017x over previous
.LBB0_718:
	s_or_b64 exec, exec, s[96:97]
	v_readlane_b32 s96, v250, 1
	s_lshl_b32 s12, s37, 7
	v_readlane_b32 s97, v250, 2
	s_lshl_b32 s12, s12, 1
	s_nop 0
	v_lshl_add_u64 v[34:35], s[96:97], 0, v[60:61]
	v_lshl_add_u64 v[34:35], v[34:35], 0, s[12:13]
	v_lshl_add_u64 v[60:61], v[128:129], 1, v[34:35]
	global_load_dwordx4 v[34:37], v[60:61], off
	global_load_dwordx4 v[168:171], v[60:61], off offset:32
	global_load_dwordx4 v[176:179], v[60:61], off offset:64
	global_load_dwordx4 v[212:215], v[60:61], off offset:96
	global_load_dwordx4 v[216:219], v[60:61], off offset:128
	global_load_dwordx4 v[220:223], v[60:61], off offset:160
	global_load_dwordx4 v[236:239], v[60:61], off offset:192
	global_load_dwordx4 v[240:243], v[60:61], off offset:224
	s_waitcnt vmcnt(7)
	v_mfma_f32_32x32x16_bf16 v[34:49], v[50:53], v[34:37], 0
	s_waitcnt vmcnt(6)
	v_mfma_f32_32x32x16_bf16 v[34:49], v[102:105], v[168:171], v[34:49]
	s_waitcnt vmcnt(5)
	v_mfma_f32_32x32x16_bf16 v[34:49], v[94:97], v[176:179], v[34:49]
	s_waitcnt vmcnt(4)
	v_mfma_f32_32x32x16_bf16 v[34:49], v[86:89], v[212:215], v[34:49]
	s_waitcnt vmcnt(3)
	v_mfma_f32_32x32x16_bf16 v[34:49], v[78:81], v[216:219], v[34:49]
	s_waitcnt vmcnt(2)
	v_mfma_f32_32x32x16_bf16 v[34:49], v[74:77], v[220:223], v[34:49]
	s_waitcnt vmcnt(1)
	v_mfma_f32_32x32x16_bf16 v[34:49], v[70:73], v[236:239], v[34:49]
	s_waitcnt vmcnt(0)
	v_mfma_f32_32x32x16_bf16 v[34:49], v[66:69], v[240:243], v[34:49]
	s_and_saveexec_b64 s[96:97], s[86:87]
	s_cbranch_execz .LBB0_720
	ds_read_b32 v60, v127
	s_nop 8
	v_mul_f32_e32 v34, 0x3db504f3, v34
	s_waitcnt lgkmcnt(0)
	v_sub_f32_e32 v60, v130, v60
	v_mul_f32_e32 v60, 0x3fb8aa3b, v60
	v_exp_f32_e32 v60, v60
	s_nop 0
	v_mul_f32_e32 v64, v34, v60

.LBB0_750:
	s_or_b64 exec, exec, s[96:97]
	v_cvt_pk_bf16_f32 v34, v34, v36
	v_add_co_u32_e32 v36, vcc, 0x36400000, v164
	v_readlane_b32 s96, v250, 1
	v_cvt_pk_bf16_f32 v35, v35, v37
	v_addc_co_u32_e32 v37, vcc, 0, v165, vcc
	v_readlane_b32 s97, v250, 2
	global_store_dwordx2 v[36:37], v[34:35], off offset:48
	s_nop 0
	v_lshl_add_u64 v[34:35], s[96:97], 0, v[58:59]
	v_lshl_add_u64 v[34:35], v[34:35], 0, s[12:13]
	v_lshl_add_u64 v[172:173], v[128:129], 1, v[34:35]
	global_load_dwordx4 v[58:61], v[172:173], off
	global_load_dwordx4 v[168:171], v[172:173], off offset:32
	global_load_dwordx4 v[176:179], v[172:173], off offset:64
	global_load_dwordx4 v[212:215], v[172:173], off offset:96
	global_load_dwordx4 v[216:219], v[172:173], off offset:128
	global_load_dwordx4 v[220:223], v[172:173], off offset:160
	global_load_dwordx4 v[236:239], v[172:173], off offset:192
	global_load_dwordx4 v[240:243], v[172:173], off offset:224
	s_waitcnt vmcnt(7)
	v_mfma_f32_32x32x16_bf16 v[34:49], v[50:53], v[58:61], 0
	s_waitcnt vmcnt(6)
	v_mfma_f32_32x32x16_bf16 v[34:49], v[102:105], v[168:171], v[34:49]
	v_mfma_f32_32x32x16_bf16 v[50:65], v[54:57], v[58:61], 0
	v_mfma_f32_32x32x16_bf16 v[50:65], v[118:121], v[168:171], v[50:65]
	s_waitcnt vmcnt(5)
	v_mfma_f32_32x32x16_bf16 v[34:49], v[94:97], v[176:179], v[34:49]
	v_mfma_f32_32x32x16_bf16 v[50:65], v[114:117], v[176:179], v[50:65]
	s_waitcnt vmcnt(4)
	v_mfma_f32_32x32x16_bf16 v[34:49], v[86:89], v[212:215], v[34:49]
	v_mfma_f32_32x32x16_bf16 v[50:65], v[110:113], v[212:215], v[50:65]
	s_waitcnt vmcnt(3)
	v_mfma_f32_32x32x16_bf16 v[34:49], v[78:81], v[216:219], v[34:49]
	v_mfma_f32_32x32x16_bf16 v[50:65], v[106:109], v[216:219], v[50:65]
	s_waitcnt vmcnt(2)
	v_mfma_f32_32x32x16_bf16 v[34:49], v[74:77], v[220:223], v[34:49]
	v_mfma_f32_32x32x16_bf16 v[50:65], v[98:101], v[220:223], v[50:65]
	s_waitcnt vmcnt(1)
	v_mfma_f32_32x32x16_bf16 v[34:49], v[70:73], v[236:239], v[34:49]
	v_mfma_f32_32x32x16_bf16 v[50:65], v[90:93], v[236:239], v[50:65]
	s_waitcnt vmcnt(0)
	v_mfma_f32_32x32x16_bf16 v[34:49], v[66:69], v[240:243], v[34:49]
	ds_read_b32 v68, v127
	v_mfma_f32_32x32x16_bf16 v[50:65], v[82:85], v[240:243], v[50:65]
	s_and_saveexec_b64 s[96:97], s[86:87]
	s_cbranch_execz .LBB0_752
	s_waitcnt lgkmcnt(14)
	v_sub_f32_e32 v66, v131, v132
	v_mul_f32_e32 v66, 0x3fb8aa3b, v66
	v_exp_f32_e32 v66, v66
	s_nop 5
	v_mul_f32_e32 v50, 0x3db504f3, v50
	v_mul_f32_e32 v167, v50, v66
